# strategy 4: one static s_setprio 1 for waves 4-7 before the SwiGLU GEMM K-loop, all 16 per-segment s_setprio flips deleted, s_setprio 0 after the loop; on top of v013
# baseline (speedup 1.0000x reference)
; #define PG8_STAGE(bufoff, gbase, voff) do { _Pragma("unroll") for (int _i = 0; _i < 2; ++_i) \
;         __builtin_amdgcn_global_load_lds((const unsigned*)((const char*)(gbase) + (voff)[_i]), (PG8_LAS unsigned*)(lds + (bufoff) + ldsw + _i * 8192), 16, 0, 0); } while (0)
; #define PG8_LDA(dst, b, h) do { _Pragma("unroll") for (int m = 0; m < 4; ++m) _Pragma("unroll") for (int k = 0; k < 2; ++k) dst[m][k] = *(const PG8_LAS bf16x8*)(lds + PG8_SA(b, h) + aoff + m * 2048 + k * 1024); } while (0)
; #define PG8_LDB(dst, b, h) do { _Pragma("unroll") for (int n = 0; n < 2; ++n) _Pragma("unroll") for (int k = 0; k < 2; ++k) dst[n][k] = *(const PG8_LAS bf16x8*)(lds + PG8_SB(b, h) + boff + n * 2048 + k * 1024); } while (0)
; #define PG8_WAIT_V(n) asm volatile("s_waitcnt vmcnt(" #n ")" ::: "memory")
; #define PG8_WAIT_L(n) asm volatile("s_waitcnt lgkmcnt(" #n ")" ::: "memory")
; #define PG8_BAR __builtin_amdgcn_s_barrier()
; template <class Epi, class Sched, bool ALIGN_EPI = false, bool SP2 = false>
; __device__ __forceinline__ void gemm_phase(PG8_LAS unsigned char* lds, const Gemm g, const Sched& S, const Epi& E) {
;     ...
;         const bool has_next = S.next(ui + 1, nxt);
;         const char* nA = has_next ? (const char*)g.A + (size_t)nxt.pm * tstep : cA; const char* nB = has_next ? (const char*)g.Bt + (size_t)nxt.pn * tstep : cB;
;         for (int t = 0; t < nt; t += 2) {
;             const bool last = (t == nt - 2);
;             const char* a1 = cA + (size_t)(t + 1) * kstep;
;             const char* a2 = last ? nA : cA + (size_t)(t + 2) * kstep; const char* b2 = last ? nB : cB + (size_t)(t + 2) * kstep;
;             const char* a3 = a2 + kstep; const char* b3 = b2 + kstep;
;             if (last && has_next) S.a_ready(nxt);
;             if constexpr (SP2) {
;             PG8_LDB(B0, 0, 0); PG8_LDB(B1, 0, 1); PG8_SCHED; PG8_LDA(At, 0, 0); PG8_STAGE(PG8_SA(1, 1), a1 + hstep, voffA);
;             PG8_WAIT_V(8); PG8_WAIT_L(0); PG8_BAR; PG8_MMA(0, 0, At, B0); PG8_MMA(0, 1, At, B1); PG8_BAR; PG8_SCHED;
;     ...
; #pragma unroll
;         for (int a = 0; a < 2; ++a)
; #pragma unroll
;             for (int b = 0; b < 2; ++b)
; #pragma unroll
;                 for (int m = 0; m < 4; ++m)
; #pragma unroll
;                     for (int n = 0; n < 2; ++n) acc[a][b][m][n] = (f32x4){0.f, 0.f, 0.f, 0.f};
;         cur = nxt; cA = nA; cB = nB; ++ui;
.LBB0_662:
	s_ashr_i32 s43, s42, 31
	s_lshl_b64 s[10:11], s[42:43], 19
	v_readlane_b32 s44, v248, 22
	v_readlane_b32 s45, v248, 23
	s_add_u32 s44, s44, s10
	s_addc_u32 s45, s45, s11
	s_and_b64 s[10:11], s[0:1], exec
	s_cselect_b32 s43, s45, s3
	s_cselect_b32 s54, s44, s2
	s_ashr_i32 s41, s40, 31
	s_lshl_b64 s[10:11], s[40:41], 19
	v_readlane_b32 s46, v247, 62
	v_readlane_b32 s47, v247, 63
	s_add_u32 s46, s46, s10
	s_addc_u32 s47, s47, s11
	s_and_b64 s[10:11], s[0:1], exec
	s_cselect_b32 s41, s47, s9
	s_cselect_b32 s55, s46, s8
	s_add_u32 s2, s2, 0x40080
	s_addc_u32 s3, s3, 0
	s_add_u32 s56, s8, 0x100
	v_mov_b32_e32 v2, 0
	s_addc_u32 s57, s9, 0
	s_mov_b32 s58, -2
	v_mov_b32_e32 v3, v2
	v_mov_b32_e32 v4, v2
	v_mov_b32_e32 v5, v2
	v_mov_b32_e32 v10, v2
	v_mov_b32_e32 v11, v2
	v_mov_b32_e32 v12, v2
	v_mov_b32_e32 v13, v2
	v_mov_b32_e32 v18, v2
	v_mov_b32_e32 v19, v2
	v_mov_b32_e32 v20, v2
	v_mov_b32_e32 v21, v2
	v_mov_b32_e32 v26, v2
	v_mov_b32_e32 v27, v2
	v_mov_b32_e32 v28, v2
	v_mov_b32_e32 v29, v2
	v_mov_b32_e32 v34, v2
	v_mov_b32_e32 v35, v2
	v_mov_b32_e32 v36, v2
	v_mov_b32_e32 v37, v2
	v_mov_b32_e32 v42, v2
	v_mov_b32_e32 v43, v2
	v_mov_b32_e32 v44, v2
	v_mov_b32_e32 v45, v2
	v_mov_b32_e32 v50, v2
	v_mov_b32_e32 v51, v2
	v_mov_b32_e32 v52, v2
	v_mov_b32_e32 v53, v2
	v_mov_b32_e32 v58, v2
	v_mov_b32_e32 v59, v2
	v_mov_b32_e32 v60, v2
	v_mov_b32_e32 v61, v2
	v_mov_b32_e32 v6, v2
	v_mov_b32_e32 v7, v2
	v_mov_b32_e32 v8, v2
	v_mov_b32_e32 v9, v2
	v_mov_b32_e32 v14, v2
	v_mov_b32_e32 v15, v2
	v_mov_b32_e32 v16, v2
	v_mov_b32_e32 v17, v2
	v_mov_b32_e32 v22, v2
	v_mov_b32_e32 v23, v2
	v_mov_b32_e32 v24, v2
	v_mov_b32_e32 v25, v2
	v_mov_b32_e32 v30, v2
	v_mov_b32_e32 v31, v2
	v_mov_b32_e32 v32, v2
	v_mov_b32_e32 v33, v2
	v_mov_b32_e32 v38, v2
	v_mov_b32_e32 v39, v2
	v_mov_b32_e32 v40, v2
	v_mov_b32_e32 v41, v2
	v_mov_b32_e32 v46, v2
	v_mov_b32_e32 v47, v2
	v_mov_b32_e32 v48, v2
	v_mov_b32_e32 v49, v2
	v_mov_b32_e32 v54, v2
	v_mov_b32_e32 v55, v2
	v_mov_b32_e32 v56, v2
	v_mov_b32_e32 v57, v2
	v_mov_b32_e32 v62, v2
	v_mov_b32_e32 v63, v2
	v_mov_b32_e32 v64, v2
	v_mov_b32_e32 v65, v2
	v_mov_b32_e32 v66, v2
	v_mov_b32_e32 v67, v2
	v_mov_b32_e32 v68, v2
	v_mov_b32_e32 v69, v2
	v_mov_b32_e32 v74, v2
	v_mov_b32_e32 v75, v2
	v_mov_b32_e32 v76, v2
	v_mov_b32_e32 v77, v2
	v_mov_b32_e32 v82, v2
	v_mov_b32_e32 v83, v2
	v_mov_b32_e32 v84, v2
	v_mov_b32_e32 v85, v2
	v_mov_b32_e32 v90, v2
	v_mov_b32_e32 v91, v2
	v_mov_b32_e32 v92, v2
	v_mov_b32_e32 v93, v2
	v_mov_b32_e32 v98, v2
	v_mov_b32_e32 v99, v2
	v_mov_b32_e32 v100, v2
	v_mov_b32_e32 v101, v2
	v_mov_b32_e32 v106, v2
	v_mov_b32_e32 v107, v2
	v_mov_b32_e32 v108, v2
	v_mov_b32_e32 v109, v2
	v_mov_b32_e32 v114, v2
	v_mov_b32_e32 v115, v2
	v_mov_b32_e32 v116, v2
	v_mov_b32_e32 v117, v2
	v_mov_b32_e32 v122, v2
	v_mov_b32_e32 v123, v2
	v_mov_b32_e32 v124, v2
	v_mov_b32_e32 v125, v2
	v_mov_b32_e32 v70, v2
	v_mov_b32_e32 v71, v2
	v_mov_b32_e32 v72, v2
	v_mov_b32_e32 v73, v2
	v_mov_b32_e32 v78, v2
	v_mov_b32_e32 v79, v2
	v_mov_b32_e32 v80, v2
	v_mov_b32_e32 v81, v2
	v_mov_b32_e32 v86, v2
	v_mov_b32_e32 v87, v2
	v_mov_b32_e32 v88, v2
	v_mov_b32_e32 v89, v2
	v_mov_b32_e32 v94, v2
	v_mov_b32_e32 v95, v2
	v_mov_b32_e32 v96, v2
	v_mov_b32_e32 v97, v2
	v_mov_b32_e32 v102, v2
	v_mov_b32_e32 v103, v2
	v_mov_b32_e32 v104, v2
	v_mov_b32_e32 v105, v2
	v_mov_b32_e32 v110, v2
	v_mov_b32_e32 v111, v2
	v_mov_b32_e32 v112, v2
	v_mov_b32_e32 v113, v2
	v_mov_b32_e32 v118, v2
	v_mov_b32_e32 v119, v2
	v_mov_b32_e32 v120, v2
	v_mov_b32_e32 v121, v2
	v_mov_b32_e32 v126, v2
	v_mov_b32_e32 v127, v2
	v_mov_b32_e32 v128, v2
	v_mov_b32_e32 v129, v2
	s_and_b64 vcc, exec, s[38:39]
	s_cbranch_vccnz .Lprio_done_l3
	s_setprio 1
.Lprio_done_l3:
.LBB0_663:
	s_add_u32 s5, s2, 0xfffc0080
	s_addc_u32 s8, s3, -1
	s_add_i32 s59, 0, 0x10000
	s_cmp_eq_u32 s58, 12
	s_cselect_b32 s11, s43, s8
	s_cselect_b32 s10, s54, s5
	s_cselect_b32 s9, s41, s57
	s_cselect_b32 s8, s55, s56
	s_add_i32 s5, 0, 0x14000
	v_add_u32_e32 v166, s59, v145
	v_add_u32_e32 v182, s5, v145
	ds_read_b128 v[140:143], v166
	ds_read_b128 v[158:161], v166 offset:1024
	ds_read_b128 v[162:165], v166 offset:2048
	ds_read_b128 v[166:169], v166 offset:3072
	ds_read_b128 v[170:173], v182
	ds_read_b128 v[174:177], v182 offset:1024
	ds_read_b128 v[178:181], v182 offset:2048
	ds_read_b128 v[182:185], v182 offset:3072
	v_lshl_add_u64 v[230:231], s[2:3], 0, v[136:137]
	s_add_i32 m0, s35, 0xc000
	ds_read_b128 v[186:189], v157
	ds_read_b128 v[190:193], v157 offset:1024
	ds_read_b128 v[194:197], v157 offset:2048
	ds_read_b128 v[198:201], v157 offset:3072
	ds_read_b128 v[214:217], v157 offset:4096
	ds_read_b128 v[218:221], v157 offset:5120
	ds_read_b128 v[222:225], v157 offset:6144
	ds_read_b128 v[226:229], v157 offset:7168
	global_load_lds_dwordx4 v[230:231], off
	v_lshl_add_u64 v[230:231], s[2:3], 0, v[138:139]
	s_add_i32 m0, s35, 0xe000
	s_nop 0
	global_load_lds_dwordx4 v[230:231], off
	s_waitcnt vmcnt(8)
	s_waitcnt lgkmcnt(0)
	s_barrier
; #define PG8_STAGE(bufoff, gbase, voff) do { _Pragma("unroll") for (int _i = 0; _i < 2; ++_i) \
;         __builtin_amdgcn_global_load_lds((const unsigned*)((const char*)(gbase) + (voff)[_i]), (PG8_LAS unsigned*)(lds + (bufoff) + ldsw + _i * 8192), 16, 0, 0); } while (0)
; #define PG8_LDA(dst, b, h) do { _Pragma("unroll") for (int m = 0; m < 4; ++m) _Pragma("unroll") for (int k = 0; k < 2; ++k) dst[m][k] = *(const PG8_LAS bf16x8*)(lds + PG8_SA(b, h) + aoff + m * 2048 + k * 1024); } while (0)
; #define PG8_LDB(dst, b, h) do { _Pragma("unroll") for (int n = 0; n < 2; ++n) _Pragma("unroll") for (int k = 0; k < 2; ++k) dst[n][k] = *(const PG8_LAS bf16x8*)(lds + PG8_SB(b, h) + boff + n * 2048 + k * 1024); } while (0)
; #define PG8_MMA(ai, bj, At, Bt) do { __builtin_amdgcn_s_setprio(1); _Pragma("unroll") for (int m = 0; m < 4; ++m) _Pragma("unroll") for (int n = 0; n < 2; ++n) _Pragma("unroll") for (int k = 0; k < 2; ++k) \
;         acc[ai][bj][m][n] = __builtin_amdgcn_mfma_f32_16x16x32_bf16(Bt[n][k], At[m][k], acc[ai][bj][m][n], 0, 0, 0); __builtin_amdgcn_s_setprio(0); } while (0)
; #define PG8_WAIT_V(n) asm volatile("s_waitcnt vmcnt(" #n ")" ::: "memory")
; #define PG8_WAIT_L(n) asm volatile("s_waitcnt lgkmcnt(" #n ")" ::: "memory")
; #define PG8_BAR __builtin_amdgcn_s_barrier()
; #define PG8_SCHED __builtin_amdgcn_sched_barrier(0)
; template <class Epi, class Sched, bool ALIGN_EPI = false, bool SP2 = false>
; __device__ __forceinline__ void gemm_phase(PG8_LAS unsigned char* lds, const Gemm g, const Sched& S, const Epi& E) {
;     ...
;             PG8_WAIT_V(8); PG8_WAIT_L(0); PG8_BAR; PG8_MMA(0, 0, At, B0); PG8_MMA(0, 1, At, B1); PG8_BAR; PG8_SCHED;
;             PG8_LDA(At, 0, 1); PG8_STAGE(PG8_SB(0, 0), b2, voffB); PG8_STAGE(PG8_SB(0, 1), b2 + hstep, voffB); PG8_STAGE(PG8_SA(0, 0), a2, voffA);
;             PG8_WAIT_V(8); PG8_WAIT_L(0); PG8_BAR; PG8_MMA(1, 0, At, B0); PG8_MMA(1, 1, At, B1); PG8_BAR; PG8_SCHED;
;             PG8_LDB(B0, 1, 0); PG8_LDB(B1, 1, 1); PG8_SCHED; PG8_LDA(At, 1, 0); PG8_STAGE(PG8_SA(0, 1), a2 + hstep, voffA);
;             PG8_WAIT_V(8); PG8_WAIT_L(0); PG8_BAR; PG8_MMA(0, 0, At, B0); PG8_MMA(0, 1, At, B1); PG8_BAR; PG8_SCHED;
	s_waitcnt lgkmcnt(0)
	v_mfma_f32_16x16x32_bf16 v[126:129], v[140:143], v[186:189], v[126:129]
	v_mfma_f32_16x16x32_bf16 v[118:121], v[162:165], v[186:189], v[118:121]
	v_mfma_f32_16x16x32_bf16 v[110:113], v[140:143], v[194:197], v[110:113]
	v_mfma_f32_16x16x32_bf16 v[102:105], v[162:165], v[194:197], v[102:105]
	v_mfma_f32_16x16x32_bf16 v[94:97], v[140:143], v[214:217], v[94:97]
	v_mfma_f32_16x16x32_bf16 v[86:89], v[162:165], v[214:217], v[86:89]
	v_mfma_f32_16x16x32_bf16 v[78:81], v[140:143], v[222:225], v[78:81]
	v_mfma_f32_16x16x32_bf16 v[70:73], v[162:165], v[222:225], v[70:73]
	v_mfma_f32_16x16x32_bf16 v[126:129], v[158:161], v[190:193], v[126:129]
	v_mfma_f32_16x16x32_bf16 v[118:121], v[166:169], v[190:193], v[118:121]
	v_mfma_f32_16x16x32_bf16 v[110:113], v[158:161], v[198:201], v[110:113]
	v_mfma_f32_16x16x32_bf16 v[102:105], v[166:169], v[198:201], v[102:105]
	v_mfma_f32_16x16x32_bf16 v[94:97], v[158:161], v[218:221], v[94:97]
	v_mfma_f32_16x16x32_bf16 v[86:89], v[166:169], v[218:221], v[86:89]
	v_mfma_f32_16x16x32_bf16 v[78:81], v[158:161], v[226:229], v[78:81]
	v_mfma_f32_16x16x32_bf16 v[70:73], v[166:169], v[226:229], v[70:73]
	v_mfma_f32_16x16x32_bf16 v[122:125], v[170:173], v[186:189], v[122:125]
	v_mfma_f32_16x16x32_bf16 v[114:117], v[178:181], v[186:189], v[114:117]
	v_mfma_f32_16x16x32_bf16 v[106:109], v[170:173], v[194:197], v[106:109]
	v_mfma_f32_16x16x32_bf16 v[98:101], v[178:181], v[194:197], v[98:101]
	v_mfma_f32_16x16x32_bf16 v[90:93], v[170:173], v[214:217], v[90:93]
	v_mfma_f32_16x16x32_bf16 v[82:85], v[178:181], v[214:217], v[82:85]
	v_mfma_f32_16x16x32_bf16 v[74:77], v[170:173], v[222:225], v[74:77]
	v_mfma_f32_16x16x32_bf16 v[66:69], v[178:181], v[222:225], v[66:69]
	v_mfma_f32_16x16x32_bf16 v[122:125], v[174:177], v[190:193], v[122:125]
	v_mfma_f32_16x16x32_bf16 v[114:117], v[182:185], v[190:193], v[114:117]
	v_mfma_f32_16x16x32_bf16 v[106:109], v[174:177], v[198:201], v[106:109]
	v_mfma_f32_16x16x32_bf16 v[98:101], v[182:185], v[198:201], v[98:101]
	v_mfma_f32_16x16x32_bf16 v[90:93], v[174:177], v[218:221], v[90:93]
	v_mfma_f32_16x16x32_bf16 v[82:85], v[182:185], v[218:221], v[82:85]
	v_mfma_f32_16x16x32_bf16 v[74:77], v[174:177], v[226:229], v[74:77]
	v_mfma_f32_16x16x32_bf16 v[66:69], v[182:185], v[226:229], v[66:69]
	s_barrier
	s_add_i32 s59, s59, s4
	v_lshl_add_u64 v[230:231], s[8:9], 0, v[0:1]
	s_mov_b32 m0, s59
	ds_read_b128 v[186:189], v157 offset:16384
	ds_read_b128 v[190:193], v157 offset:17408
	ds_read_b128 v[194:197], v157 offset:18432
	ds_read_b128 v[198:201], v157 offset:19456
	ds_read_b128 v[214:217], v157 offset:20480
	ds_read_b128 v[218:221], v157 offset:21504
	ds_read_b128 v[222:225], v157 offset:22528
	ds_read_b128 v[226:229], v157 offset:23552
	global_load_lds_dwordx4 v[230:231], off
	s_add_i32 m0, s59, 0x2000
	s_add_u32 s60, s8, 0x40000
	v_lshl_add_u64 v[232:233], s[8:9], 0, v[130:131]
	s_addc_u32 s61, s9, 0
	s_add_i32 s5, s5, s4
	global_load_lds_dwordx4 v[232:233], off
	v_lshl_add_u64 v[234:235], s[60:61], 0, v[0:1]
	s_mov_b32 m0, s5
	v_lshl_add_u64 v[236:237], s[10:11], 0, v[132:133]
	global_load_lds_dwordx4 v[234:235], off
	v_lshl_add_u64 v[234:235], s[60:61], 0, v[130:131]
	s_add_i32 m0, s5, 0x2000
	s_nop 0
	global_load_lds_dwordx4 v[234:235], off
	v_lshl_add_u64 v[234:235], s[10:11], 0, v[134:135]
	s_mov_b32 m0, s35
	s_nop 0
	global_load_lds_dwordx4 v[234:235], off
	s_mov_b32 m0, s48
	s_nop 0
	global_load_lds_dwordx4 v[236:237], off
	s_waitcnt vmcnt(8)
	s_waitcnt lgkmcnt(0)
	s_barrier
	s_waitcnt lgkmcnt(0)
	v_mfma_f32_16x16x32_bf16 v[62:65], v[140:143], v[186:189], v[62:65]
	v_mfma_f32_16x16x32_bf16 v[54:57], v[162:165], v[186:189], v[54:57]
	v_mfma_f32_16x16x32_bf16 v[46:49], v[140:143], v[194:197], v[46:49]
	v_mfma_f32_16x16x32_bf16 v[38:41], v[162:165], v[194:197], v[38:41]
	v_mfma_f32_16x16x32_bf16 v[30:33], v[140:143], v[214:217], v[30:33]
	v_mfma_f32_16x16x32_bf16 v[22:25], v[162:165], v[214:217], v[22:25]
	v_mfma_f32_16x16x32_bf16 v[14:17], v[140:143], v[222:225], v[14:17]
	v_mfma_f32_16x16x32_bf16 v[6:9], v[162:165], v[222:225], v[6:9]
	v_mfma_f32_16x16x32_bf16 v[62:65], v[158:161], v[190:193], v[62:65]
	v_mfma_f32_16x16x32_bf16 v[54:57], v[166:169], v[190:193], v[54:57]
	v_mfma_f32_16x16x32_bf16 v[46:49], v[158:161], v[198:201], v[46:49]
	v_mfma_f32_16x16x32_bf16 v[38:41], v[166:169], v[198:201], v[38:41]
	v_mfma_f32_16x16x32_bf16 v[30:33], v[158:161], v[218:221], v[30:33]
	v_mfma_f32_16x16x32_bf16 v[22:25], v[166:169], v[218:221], v[22:25]
	v_mfma_f32_16x16x32_bf16 v[14:17], v[158:161], v[226:229], v[14:17]
	v_mfma_f32_16x16x32_bf16 v[6:9], v[166:169], v[226:229], v[6:9]
	v_mfma_f32_16x16x32_bf16 v[58:61], v[170:173], v[186:189], v[58:61]
	v_mfma_f32_16x16x32_bf16 v[50:53], v[178:181], v[186:189], v[50:53]
	v_mfma_f32_16x16x32_bf16 v[42:45], v[170:173], v[194:197], v[42:45]
	v_mfma_f32_16x16x32_bf16 v[34:37], v[178:181], v[194:197], v[34:37]
	v_mfma_f32_16x16x32_bf16 v[26:29], v[170:173], v[214:217], v[26:29]
	v_mfma_f32_16x16x32_bf16 v[18:21], v[178:181], v[214:217], v[18:21]
	v_mfma_f32_16x16x32_bf16 v[10:13], v[170:173], v[222:225], v[10:13]
	v_mfma_f32_16x16x32_bf16 v[2:5], v[178:181], v[222:225], v[2:5]
	v_mfma_f32_16x16x32_bf16 v[58:61], v[174:177], v[190:193], v[58:61]
	v_mfma_f32_16x16x32_bf16 v[50:53], v[182:185], v[190:193], v[50:53]
	v_mfma_f32_16x16x32_bf16 v[42:45], v[174:177], v[198:201], v[42:45]
	v_mfma_f32_16x16x32_bf16 v[34:37], v[182:185], v[198:201], v[34:37]
	v_mfma_f32_16x16x32_bf16 v[26:29], v[174:177], v[218:221], v[26:29]
	v_mfma_f32_16x16x32_bf16 v[18:21], v[182:185], v[218:221], v[18:21]
	v_mfma_f32_16x16x32_bf16 v[10:13], v[174:177], v[226:229], v[10:13]
	v_mfma_f32_16x16x32_bf16 v[2:5], v[182:185], v[226:229], v[2:5]
	s_barrier
; #define PG8_STAGE(bufoff, gbase, voff) do { _Pragma("unroll") for (int _i = 0; _i < 2; ++_i) \
;         __builtin_amdgcn_global_load_lds((const unsigned*)((const char*)(gbase) + (voff)[_i]), (PG8_LAS unsigned*)(lds + (bufoff) + ldsw + _i * 8192), 16, 0, 0); } while (0)
; #define PG8_LDA(dst, b, h) do { _Pragma("unroll") for (int m = 0; m < 4; ++m) _Pragma("unroll") for (int k = 0; k < 2; ++k) dst[m][k] = *(const PG8_LAS bf16x8*)(lds + PG8_SA(b, h) + aoff + m * 2048 + k * 1024); } while (0)
; #define PG8_MMA(ai, bj, At, Bt) do { __builtin_amdgcn_s_setprio(1); _Pragma("unroll") for (int m = 0; m < 4; ++m) _Pragma("unroll") for (int n = 0; n < 2; ++n) _Pragma("unroll") for (int k = 0; k < 2; ++k) \
;         acc[ai][bj][m][n] = __builtin_amdgcn_mfma_f32_16x16x32_bf16(Bt[n][k], At[m][k], acc[ai][bj][m][n], 0, 0, 0); __builtin_amdgcn_s_setprio(0); } while (0)
; #define PG8_WAIT_V(n) asm volatile("s_waitcnt vmcnt(" #n ")" ::: "memory")
; #define PG8_WAIT_L(n) asm volatile("s_waitcnt lgkmcnt(" #n ")" ::: "memory")
; #define PG8_BAR __builtin_amdgcn_s_barrier()
; #define PG8_SCHED __builtin_amdgcn_sched_barrier(0)
; template <class Epi, class Sched, bool ALIGN_EPI = false, bool SP2 = false>
; __device__ __forceinline__ void gemm_phase(PG8_LAS unsigned char* lds, const Gemm g, const Sched& S, const Epi& E) {
;     ...
;             PG8_LDA(At, 1, 1); PG8_STAGE(PG8_SB(1, 0), b3, voffB); PG8_STAGE(PG8_SB(1, 1), b3 + hstep, voffB); PG8_STAGE(PG8_SA(1, 0), a3, voffA);
;             PG8_WAIT_V(8); PG8_WAIT_L(0); PG8_BAR; PG8_MMA(1, 0, At, B0); PG8_MMA(1, 1, At, B1); PG8_BAR; PG8_SCHED;
	s_add_i32 s5, 0, 0x18000
	v_add_u32_e32 v166, s5, v145
	v_add_u32_e32 v182, s29, v145
	ds_read_b128 v[140:143], v166
	ds_read_b128 v[158:161], v166 offset:1024
	ds_read_b128 v[162:165], v166 offset:2048
	ds_read_b128 v[166:169], v166 offset:3072
	ds_read_b128 v[170:173], v182
	ds_read_b128 v[174:177], v182 offset:1024
	ds_read_b128 v[178:181], v182 offset:2048
	ds_read_b128 v[182:185], v182 offset:3072
	s_add_u32 s10, s10, 0x40000
	s_addc_u32 s11, s11, 0
	s_mov_b32 m0, s49
	v_lshl_add_u64 v[238:239], s[10:11], 0, v[134:135]
	ds_read_b128 v[186:189], v157 offset:32768
	ds_read_b128 v[190:193], v157 offset:33792
	ds_read_b128 v[194:197], v157 offset:34816
	ds_read_b128 v[198:201], v157 offset:35840
	ds_read_b128 v[214:217], v157 offset:36864
	ds_read_b128 v[218:221], v157 offset:37888
	ds_read_b128 v[222:225], v157 offset:38912
	ds_read_b128 v[226:229], v157 offset:39936
	global_load_lds_dwordx4 v[238:239], off
	v_lshl_add_u64 v[238:239], s[10:11], 0, v[132:133]
	s_mov_b32 m0, s50
	s_nop 0
	global_load_lds_dwordx4 v[238:239], off
	s_waitcnt vmcnt(8)
	s_waitcnt lgkmcnt(0)
	s_barrier
	s_waitcnt lgkmcnt(0)
	v_mfma_f32_16x16x32_bf16 v[126:129], v[140:143], v[186:189], v[126:129]
	v_mfma_f32_16x16x32_bf16 v[118:121], v[162:165], v[186:189], v[118:121]
	v_mfma_f32_16x16x32_bf16 v[110:113], v[140:143], v[194:197], v[110:113]
	v_mfma_f32_16x16x32_bf16 v[102:105], v[162:165], v[194:197], v[102:105]
	v_mfma_f32_16x16x32_bf16 v[94:97], v[140:143], v[214:217], v[94:97]
	v_mfma_f32_16x16x32_bf16 v[86:89], v[162:165], v[214:217], v[86:89]
	v_mfma_f32_16x16x32_bf16 v[78:81], v[140:143], v[222:225], v[78:81]
	v_mfma_f32_16x16x32_bf16 v[70:73], v[162:165], v[222:225], v[70:73]
	v_mfma_f32_16x16x32_bf16 v[126:129], v[158:161], v[190:193], v[126:129]
	v_mfma_f32_16x16x32_bf16 v[118:121], v[166:169], v[190:193], v[118:121]
	v_mfma_f32_16x16x32_bf16 v[110:113], v[158:161], v[198:201], v[110:113]
	v_mfma_f32_16x16x32_bf16 v[102:105], v[166:169], v[198:201], v[102:105]
	v_mfma_f32_16x16x32_bf16 v[94:97], v[158:161], v[218:221], v[94:97]
	v_mfma_f32_16x16x32_bf16 v[86:89], v[166:169], v[218:221], v[86:89]
	v_mfma_f32_16x16x32_bf16 v[78:81], v[158:161], v[226:229], v[78:81]
	v_mfma_f32_16x16x32_bf16 v[70:73], v[166:169], v[226:229], v[70:73]
	v_mfma_f32_16x16x32_bf16 v[122:125], v[170:173], v[186:189], v[122:125]
	v_mfma_f32_16x16x32_bf16 v[114:117], v[178:181], v[186:189], v[114:117]
	v_mfma_f32_16x16x32_bf16 v[106:109], v[170:173], v[194:197], v[106:109]
	v_mfma_f32_16x16x32_bf16 v[98:101], v[178:181], v[194:197], v[98:101]
	v_mfma_f32_16x16x32_bf16 v[90:93], v[170:173], v[214:217], v[90:93]
	v_mfma_f32_16x16x32_bf16 v[82:85], v[178:181], v[214:217], v[82:85]
	v_mfma_f32_16x16x32_bf16 v[74:77], v[170:173], v[222:225], v[74:77]
	v_mfma_f32_16x16x32_bf16 v[66:69], v[178:181], v[222:225], v[66:69]
	v_mfma_f32_16x16x32_bf16 v[122:125], v[174:177], v[190:193], v[122:125]
	v_mfma_f32_16x16x32_bf16 v[114:117], v[182:185], v[190:193], v[114:117]
	v_mfma_f32_16x16x32_bf16 v[106:109], v[174:177], v[198:201], v[106:109]
	v_mfma_f32_16x16x32_bf16 v[98:101], v[182:185], v[198:201], v[98:101]
	v_mfma_f32_16x16x32_bf16 v[90:93], v[174:177], v[218:221], v[90:93]
	v_mfma_f32_16x16x32_bf16 v[82:85], v[182:185], v[218:221], v[82:85]
	v_mfma_f32_16x16x32_bf16 v[74:77], v[174:177], v[226:229], v[74:77]
	v_mfma_f32_16x16x32_bf16 v[66:69], v[182:185], v[226:229], v[66:69]
	s_barrier
; #define PG8_STAGE(bufoff, gbase, voff) do { _Pragma("unroll") for (int _i = 0; _i < 2; ++_i) \
;         __builtin_amdgcn_global_load_lds((const unsigned*)((const char*)(gbase) + (voff)[_i]), (PG8_LAS unsigned*)(lds + (bufoff) + ldsw + _i * 8192), 16, 0, 0); } while (0)
; #define PG8_LDA(dst, b, h) do { _Pragma("unroll") for (int m = 0; m < 4; ++m) _Pragma("unroll") for (int k = 0; k < 2; ++k) dst[m][k] = *(const PG8_LAS bf16x8*)(lds + PG8_SA(b, h) + aoff + m * 2048 + k * 1024); } while (0)
; #define PG8_MMA(ai, bj, At, Bt) do { __builtin_amdgcn_s_setprio(1); _Pragma("unroll") for (int m = 0; m < 4; ++m) _Pragma("unroll") for (int n = 0; n < 2; ++n) _Pragma("unroll") for (int k = 0; k < 2; ++k) \
;         acc[ai][bj][m][n] = __builtin_amdgcn_mfma_f32_16x16x32_bf16(Bt[n][k], At[m][k], acc[ai][bj][m][n], 0, 0, 0); __builtin_amdgcn_s_setprio(0); } while (0)
; #define PG8_WAIT_V(n) asm volatile("s_waitcnt vmcnt(" #n ")" ::: "memory")
; #define PG8_WAIT_L(n) asm volatile("s_waitcnt lgkmcnt(" #n ")" ::: "memory")
; #define PG8_BAR __builtin_amdgcn_s_barrier()
; #define PG8_SCHED __builtin_amdgcn_sched_barrier(0)
; template <class Epi, class Sched, bool ALIGN_EPI = false, bool SP2 = false>
; __device__ __forceinline__ void gemm_phase(PG8_LAS unsigned char* lds, const Gemm g, const Sched& S, const Epi& E) {
;     ...
;         for (int t = 0; t < nt; t += 2) {
;     ...
;             PG8_LDA(At, 1, 1); PG8_STAGE(PG8_SB(1, 0), b3, voffB); PG8_STAGE(PG8_SB(1, 1), b3 + hstep, voffB); PG8_STAGE(PG8_SA(1, 0), a3, voffA);
;             PG8_WAIT_V(8); PG8_WAIT_L(0); PG8_BAR; PG8_MMA(1, 0, At, B0); PG8_MMA(1, 1, At, B1); PG8_BAR; PG8_SCHED;
	s_add_i32 s5, s5, s4
	v_lshl_add_u64 v[230:231], v[230:231], 0, s[30:31]
	s_mov_b32 m0, s5
	ds_read_b128 v[186:189], v157 offset:49152
	ds_read_b128 v[190:193], v157 offset:50176
	ds_read_b128 v[194:197], v157 offset:51200
	ds_read_b128 v[198:201], v157 offset:52224
	ds_read_b128 v[214:217], v157 offset:53248
	ds_read_b128 v[218:221], v157 offset:54272
	ds_read_b128 v[222:225], v157 offset:55296
	ds_read_b128 v[226:229], v157 offset:56320
	global_load_lds_dwordx4 v[230:231], off
	s_add_i32 m0, s5, 0x2000
	s_add_u32 s8, s8, 0x40080
	v_lshl_add_u64 v[230:231], v[232:233], 0, s[30:31]
	s_addc_u32 s9, s9, 0
	s_add_i32 s5, s29, s4
	global_load_lds_dwordx4 v[230:231], off
	v_lshl_add_u64 v[230:231], s[8:9], 0, v[0:1]
	s_mov_b32 m0, s5
	s_nop 0
	global_load_lds_dwordx4 v[230:231], off
	v_lshl_add_u64 v[230:231], s[8:9], 0, v[130:131]
	s_add_i32 m0, s5, 0x2000
	s_nop 0
	global_load_lds_dwordx4 v[230:231], off
	v_lshl_add_u64 v[230:231], v[234:235], 0, s[30:31]
	s_mov_b32 m0, s51
	s_nop 0
	global_load_lds_dwordx4 v[230:231], off
	v_lshl_add_u64 v[230:231], v[236:237], 0, s[30:31]
	s_mov_b32 m0, s52
	s_nop 0
	global_load_lds_dwordx4 v[230:231], off
	s_waitcnt vmcnt(8)
	s_waitcnt lgkmcnt(0)
	s_barrier
	s_waitcnt lgkmcnt(0)
	v_mfma_f32_16x16x32_bf16 v[62:65], v[140:143], v[186:189], v[62:65]
	v_mfma_f32_16x16x32_bf16 v[54:57], v[162:165], v[186:189], v[54:57]
	v_mfma_f32_16x16x32_bf16 v[46:49], v[140:143], v[194:197], v[46:49]
	v_mfma_f32_16x16x32_bf16 v[38:41], v[162:165], v[194:197], v[38:41]
	v_mfma_f32_16x16x32_bf16 v[30:33], v[140:143], v[214:217], v[30:33]
	v_mfma_f32_16x16x32_bf16 v[22:25], v[162:165], v[214:217], v[22:25]
	v_mfma_f32_16x16x32_bf16 v[14:17], v[140:143], v[222:225], v[14:17]
	v_mfma_f32_16x16x32_bf16 v[6:9], v[162:165], v[222:225], v[6:9]
	v_mfma_f32_16x16x32_bf16 v[62:65], v[158:161], v[190:193], v[62:65]
	v_mfma_f32_16x16x32_bf16 v[54:57], v[166:169], v[190:193], v[54:57]
	v_mfma_f32_16x16x32_bf16 v[46:49], v[158:161], v[198:201], v[46:49]
	v_mfma_f32_16x16x32_bf16 v[38:41], v[166:169], v[198:201], v[38:41]
	v_mfma_f32_16x16x32_bf16 v[30:33], v[158:161], v[218:221], v[30:33]
	v_mfma_f32_16x16x32_bf16 v[22:25], v[166:169], v[218:221], v[22:25]
	v_mfma_f32_16x16x32_bf16 v[14:17], v[158:161], v[226:229], v[14:17]
	v_mfma_f32_16x16x32_bf16 v[6:9], v[166:169], v[226:229], v[6:9]
	v_mfma_f32_16x16x32_bf16 v[58:61], v[170:173], v[186:189], v[58:61]
	v_mfma_f32_16x16x32_bf16 v[50:53], v[178:181], v[186:189], v[50:53]
	v_mfma_f32_16x16x32_bf16 v[42:45], v[170:173], v[194:197], v[42:45]
	v_mfma_f32_16x16x32_bf16 v[34:37], v[178:181], v[194:197], v[34:37]
	v_mfma_f32_16x16x32_bf16 v[26:29], v[170:173], v[214:217], v[26:29]
	v_mfma_f32_16x16x32_bf16 v[18:21], v[178:181], v[214:217], v[18:21]
	v_mfma_f32_16x16x32_bf16 v[10:13], v[170:173], v[222:225], v[10:13]
	v_mfma_f32_16x16x32_bf16 v[2:5], v[178:181], v[222:225], v[2:5]
	v_mfma_f32_16x16x32_bf16 v[58:61], v[174:177], v[190:193], v[58:61]
	v_mfma_f32_16x16x32_bf16 v[50:53], v[182:185], v[190:193], v[50:53]
	v_mfma_f32_16x16x32_bf16 v[42:45], v[174:177], v[198:201], v[42:45]
	v_mfma_f32_16x16x32_bf16 v[34:37], v[182:185], v[198:201], v[34:37]
	v_mfma_f32_16x16x32_bf16 v[26:29], v[174:177], v[218:221], v[26:29]
	v_mfma_f32_16x16x32_bf16 v[18:21], v[182:185], v[218:221], v[18:21]
	v_mfma_f32_16x16x32_bf16 v[10:13], v[174:177], v[226:229], v[10:13]
	v_mfma_f32_16x16x32_bf16 v[2:5], v[182:185], v[226:229], v[2:5]
	s_barrier
	s_add_i32 s58, s58, 2
	s_add_u32 s2, s2, 0x100
	s_addc_u32 s3, s3, 0
	s_add_u32 s56, s56, 0x100
	s_addc_u32 s57, s57, 0
	s_cmp_gt_u32 s58, 13
	s_cbranch_scc0 .LBB0_663
	s_setprio 0
	s_and_b64 vcc, exec, s[38:39]
	s_cbranch_vccz .LBB0_666
	s_barrier
